# v18: v9 + P7 item order in three workgroup groups by blockIdx mod 3 (sample,sample,prompt / prompt,sample,sample / sample,prompt,sample)
# baseline (speedup 1.0000x reference)
; #define LAS __attribute__((address_space(3)))
; DI void lbar() { asm volatile("s_waitcnt lgkmcnt(0)" ::: "memory"); __builtin_amdgcn_s_barrier(); asm volatile("" ::: "memory"); }
; DI void attn_sample_item(const Params& p, int item, ldsp lds, int tid_) {
;     ...
; #pragma unroll
;   for (int j = 0; j < 16; ++j) vvB[j] = __builtin_nontemporal_load((const f32x4*)(cv + (size_t)(wid * 32 + 16 + j) * 1024 + lane * 4));
;   lbar();
;   {
;     f32x4 acc[4];
; #pragma unroll
;     for (int t = 0; t < 4; ++t) acc[t] = (f32x4){0.f, 0.f, 0.f, 0.f};
; #pragma unroll
;     for (int t = 0; t < 4; ++t)
; #pragma unroll
;       for (int j4 = 0; j4 < 4; ++j4) { const f32x4 pp = *(const LAS f32x4*)(SC + t * 256 + wid * 32 + j4 * 4);
; #pragma unroll
;         for (int e = 0; e < 4; ++e) acc[t] += pp[e] * vvA[j4 * 4 + e]; }
; DI void phase_attn(const Params& p, ldsp lds, int tid) {
;   const int G = gridDim.x;
;   if (blockIdx.x & 1) for (int j = blockIdx.x; j < 512; j += G) attn_sample_item(p, j, lds, tid);
;   for (int i = blockIdx.x; i < 256; i += G) attn_prompt_item(p, i, lds, tid);
;   if (!(blockIdx.x & 1)) for (int j = blockIdx.x; j < 512; j += G) attn_sample_item(p, j, lds, tid);
.LBB0_1601:
	s_or_b64 exec, exec, s[4:5]
	s_mul_i32 s98, s2, 0xaaab
	s_lshr_b32 s98, s98, 17
	s_mul_i32 s98, s98, 3
	s_sub_i32 s98, s2, s98
	s_movk_i32 s99, 0x200
	s_cmp_eq_u32 s98, 2
	s_cselect_b32 s99, 0x100, s99
	s_cmp_eq_u32 s98, 1
	s_cselect_b64 s[24:25], -1, 0
	s_cmpk_gt_i32 s2, 0x1ff
	s_cselect_b64 s[0:1], -1, 0
	s_or_b64 s[0:1], s[0:1], s[24:25]
	s_load_dwordx4 s[12:15], s[72:73], 0x30
	s_add_u32 s36, s42, 0x15768000
	s_addc_u32 s37, s43, 0
	s_add_u32 s22, s42, 0x2100000
	s_mov_b32 s27, 0
	s_addc_u32 s23, s43, 0
	s_and_b64 vcc, exec, s[0:1]
	s_waitcnt lgkmcnt(0)
	s_barrier
	s_cbranch_vccnz .LBB0_1670
	v_mbcnt_hi_u32_b32 v214, -1, v213
	v_and_b32_e32 v0, 64, v214
	s_lshl_b32 s0, s2, 8
	s_lshl_b32 s1, s94, 8
	v_mov_b32_e32 v145, 0
	s_mov_b32 s3, 0x200000
	s_mov_b32 s33, 0x400000
	s_mov_b32 s38, 0x600000
	v_xor_b32_e32 v215, 1, v214
	v_add_u32_e32 v216, 64, v0
	v_xor_b32_e32 v217, 2, v214
	v_xor_b32_e32 v218, 4, v214
	v_xor_b32_e32 v219, 8, v214
	v_xor_b32_e32 v220, 16, v214
	v_xor_b32_e32 v221, 32, v214
	s_mov_b32 s39, 0xf149f2ca
	s_mov_b32 s40, s2
	s_branch .LBB0_1604
.LBB0_1603:
	s_or_b64 exec, exec, s[4:5]
	v_lshl_add_u64 v[2:3], v[0:1], 0, v[146:147]
	v_lshl_add_u64 v[4:5], v[0:1], 0, v[148:149]
	global_load_dwordx4 v[40:43], v[2:3], off nt
	global_load_dwordx4 v[36:39], v[4:5], off nt
	v_lshl_add_u64 v[2:3], v[0:1], 0, v[150:151]
	v_lshl_add_u64 v[4:5], v[0:1], 0, v[152:153]
	global_load_dwordx4 v[48:51], v[2:3], off nt
	global_load_dwordx4 v[44:47], v[4:5], off nt
	v_lshl_add_u64 v[2:3], v[0:1], 0, v[154:155]
	v_lshl_add_u64 v[4:5], v[0:1], 0, v[156:157]
	global_load_dwordx4 v[56:59], v[2:3], off nt
	global_load_dwordx4 v[52:55], v[4:5], off nt
	v_lshl_add_u64 v[2:3], v[0:1], 0, v[158:159]
	v_lshl_add_u64 v[4:5], v[0:1], 0, v[160:161]
	global_load_dwordx4 v[60:63], v[2:3], off nt
	global_load_dwordx4 v[32:35], v[4:5], off nt
	v_lshl_add_u64 v[2:3], v[0:1], 0, v[164:165]
	v_lshl_add_u64 v[4:5], v[0:1], 0, v[170:171]
	global_load_dwordx4 v[12:15], v[2:3], off nt
	s_nop 0
	global_load_dwordx4 v[4:7], v[4:5], off nt
	v_lshl_add_u64 v[2:3], v[0:1], 0, v[174:175]
	v_lshl_add_u64 v[8:9], v[0:1], 0, v[178:179]
	global_load_dwordx4 v[20:23], v[2:3], off nt
	s_nop 0
	global_load_dwordx4 v[8:11], v[8:9], off nt
	v_lshl_add_u64 v[2:3], v[0:1], 0, v[184:185]
	v_lshl_add_u64 v[16:17], v[0:1], 0, v[188:189]
	global_load_dwordx4 v[24:27], v[2:3], off nt
	s_nop 0
	global_load_dwordx4 v[16:19], v[16:17], off nt
	v_lshl_add_u64 v[2:3], v[0:1], 0, v[192:193]
	v_lshl_add_u64 v[0:1], v[0:1], 0, v[196:197]
	global_load_dwordx4 v[28:31], v[2:3], off nt
	s_nop 0
	global_load_dwordx4 v[0:3], v[0:1], off nt
	s_waitcnt lgkmcnt(0)
	s_barrier
	ds_read_b128 v[128:131], v136
	ds_read_b128 v[132:135], v136 offset:16
	ds_read_b128 v[138:141], v136 offset:32
	ds_read_b128 v[146:149], v136 offset:48
	s_add_i32 s4, s28, 0x4000
	s_waitcnt vmcnt(31) lgkmcnt(3)
	v_pk_fma_f32 v[142:143], v[100:101], v[128:129], 0 op_sel_hi:[1,0,0]
	v_pk_fma_f32 v[150:151], v[102:103], v[128:129], 0 op_sel_hi:[1,0,0]
	s_lshl_b32 s26, s26, 1
	s_waitcnt vmcnt(30)
	v_pk_fma_f32 v[150:151], v[94:95], v[128:129], v[150:151] op_sel:[0,1,0]
	v_pk_fma_f32 v[128:129], v[92:93], v[128:129], v[142:143] op_sel:[0,1,0]
	s_waitcnt vmcnt(29)
	v_pk_fma_f32 v[142:143], v[114:115], v[130:131], v[150:151] op_sel_hi:[1,0,1]
	v_pk_fma_f32 v[128:129], v[112:113], v[130:131], v[128:129] op_sel_hi:[1,0,1]
	v_mov_b32_e32 v130, v131
	s_waitcnt vmcnt(28)
	v_pk_fma_f32 v[128:129], v[108:109], v[130:131], v[128:129] op_sel_hi:[1,0,1]
	v_pk_fma_f32 v[130:131], v[110:111], v[130:131], v[142:143] op_sel_hi:[1,0,1]
	s_waitcnt vmcnt(27) lgkmcnt(2)
	v_pk_fma_f32 v[128:129], v[120:121], v[132:133], v[128:129] op_sel_hi:[1,0,1]
	v_pk_fma_f32 v[130:131], v[122:123], v[132:133], v[130:131] op_sel_hi:[1,0,1]
	s_waitcnt vmcnt(26)
	v_pk_fma_f32 v[128:129], v[116:117], v[132:133], v[128:129] op_sel:[0,1,0]
	v_pk_fma_f32 v[130:131], v[118:119], v[132:133], v[130:131] op_sel:[0,1,0]
	s_waitcnt vmcnt(25)
	v_pk_fma_f32 v[128:129], v[124:125], v[134:135], v[128:129] op_sel_hi:[1,0,1]
	v_pk_fma_f32 v[130:131], v[126:127], v[134:135], v[130:131] op_sel_hi:[1,0,1]
	v_mov_b32_e32 v132, v135
	s_waitcnt vmcnt(24)
	v_pk_fma_f32 v[128:129], v[104:105], v[132:133], v[128:129] op_sel_hi:[1,0,1]
	v_pk_fma_f32 v[130:131], v[106:107], v[132:133], v[130:131] op_sel_hi:[1,0,1]
	s_waitcnt vmcnt(23) lgkmcnt(1)
	v_pk_fma_f32 v[128:129], v[68:69], v[138:139], v[128:129] op_sel_hi:[1,0,1]
	v_pk_fma_f32 v[130:131], v[70:71], v[138:139], v[130:131] op_sel_hi:[1,0,1]
	s_waitcnt vmcnt(22)
	v_pk_fma_f32 v[128:129], v[64:65], v[138:139], v[128:129] op_sel:[0,1,0]
	v_pk_fma_f32 v[130:131], v[66:67], v[138:139], v[130:131] op_sel:[0,1,0]
	s_waitcnt vmcnt(21)
	v_pk_fma_f32 v[128:129], v[80:81], v[140:141], v[128:129] op_sel_hi:[1,0,1]
	v_pk_fma_f32 v[130:131], v[82:83], v[140:141], v[130:131] op_sel_hi:[1,0,1]
	v_mov_b32_e32 v132, v141
	s_waitcnt vmcnt(20)
	v_pk_fma_f32 v[128:129], v[76:77], v[132:133], v[128:129] op_sel_hi:[1,0,1]
	v_pk_fma_f32 v[130:131], v[78:79], v[132:133], v[130:131] op_sel_hi:[1,0,1]
	s_waitcnt vmcnt(19) lgkmcnt(0)
	v_pk_fma_f32 v[128:129], v[88:89], v[146:147], v[128:129] op_sel_hi:[1,0,1]
	v_pk_fma_f32 v[130:131], v[90:91], v[146:147], v[130:131] op_sel_hi:[1,0,1]
	s_waitcnt vmcnt(18)
	v_pk_fma_f32 v[128:129], v[84:85], v[146:147], v[128:129] op_sel:[0,1,0]
	v_pk_fma_f32 v[130:131], v[86:87], v[146:147], v[130:131] op_sel:[0,1,0]
	s_waitcnt vmcnt(17)
	v_pk_fma_f32 v[134:135], v[96:97], v[148:149], v[128:129] op_sel_hi:[1,0,1]
	v_pk_fma_f32 v[132:133], v[98:99], v[148:149], v[130:131] op_sel_hi:[1,0,1]
	ds_read_b128 v[128:131], v136 offset:1024
	v_mov_b32_e32 v138, v149
	s_waitcnt vmcnt(16)
; #define LAS __attribute__((address_space(3)))
; DI void attn_sample_item(const Params& p, int item, ldsp lds, int tid_) {
;     ...
; #pragma unroll
;     for (int t = 0; t < 4; ++t)
; #pragma unroll
;       for (int j4 = 0; j4 < 4; ++j4) { const f32x4 pp = *(const LAS f32x4*)(SC + t * 256 + wid * 32 + j4 * 4);
; #pragma unroll
;         for (int e = 0; e < 4; ++e) acc[t] += pp[e] * vvA[j4 * 4 + e]; }
	v_pk_fma_f32 v[142:143], v[72:73], v[138:139], v[134:135] op_sel_hi:[1,0,1]
	v_pk_fma_f32 v[150:151], v[74:75], v[138:139], v[132:133] op_sel_hi:[1,0,1]
	ds_read_b128 v[132:135], v136 offset:1040
	s_waitcnt lgkmcnt(1)
	v_pk_fma_f32 v[138:139], v[100:101], v[128:129], 0 op_sel_hi:[1,0,0]
	v_pk_fma_f32 v[140:141], v[102:103], v[128:129], 0 op_sel_hi:[1,0,0]
	ds_read_b128 v[146:149], v136 offset:2064
	v_pk_fma_f32 v[140:141], v[94:95], v[128:129], v[140:141] op_sel:[0,1,0]
	v_pk_fma_f32 v[128:129], v[92:93], v[128:129], v[138:139] op_sel:[0,1,0]
	v_pk_fma_f32 v[138:139], v[114:115], v[130:131], v[140:141] op_sel_hi:[1,0,1]
	v_pk_fma_f32 v[128:129], v[112:113], v[130:131], v[128:129] op_sel_hi:[1,0,1]
	v_mov_b32_e32 v130, v131
	v_pk_fma_f32 v[128:129], v[108:109], v[130:131], v[128:129] op_sel_hi:[1,0,1]
	v_pk_fma_f32 v[130:131], v[110:111], v[130:131], v[138:139] op_sel_hi:[1,0,1]
	s_waitcnt lgkmcnt(1)
	v_pk_fma_f32 v[128:129], v[120:121], v[132:133], v[128:129] op_sel_hi:[1,0,1]
	v_pk_fma_f32 v[130:131], v[122:123], v[132:133], v[130:131] op_sel_hi:[1,0,1]
	v_pk_fma_f32 v[128:129], v[116:117], v[132:133], v[128:129] op_sel:[0,1,0]
	v_pk_fma_f32 v[130:131], v[118:119], v[132:133], v[130:131] op_sel:[0,1,0]
	v_pk_fma_f32 v[138:139], v[124:125], v[134:135], v[128:129] op_sel_hi:[1,0,1]
	v_pk_fma_f32 v[132:133], v[126:127], v[134:135], v[130:131] op_sel_hi:[1,0,1]
	ds_read_b128 v[128:131], v136 offset:1056
	v_mov_b32_e32 v134, v135
	v_pk_fma_f32 v[138:139], v[104:105], v[134:135], v[138:139] op_sel_hi:[1,0,1]
	v_pk_fma_f32 v[140:141], v[106:107], v[134:135], v[132:133] op_sel_hi:[1,0,1]
	ds_read_b128 v[132:135], v136 offset:1072
	s_waitcnt lgkmcnt(1)
	v_pk_fma_f32 v[140:141], v[70:71], v[128:129], v[140:141] op_sel_hi:[1,0,1]
	v_pk_fma_f32 v[138:139], v[68:69], v[128:129], v[138:139] op_sel_hi:[1,0,1]
	s_add_i32 s40, s40, s94
	v_pk_fma_f32 v[138:139], v[64:65], v[128:129], v[138:139] op_sel:[0,1,0]
	v_pk_fma_f32 v[128:129], v[66:67], v[128:129], v[140:141] op_sel:[0,1,0]
	v_pk_fma_f32 v[138:139], v[80:81], v[130:131], v[138:139] op_sel_hi:[1,0,1]
	v_pk_fma_f32 v[128:129], v[82:83], v[130:131], v[128:129] op_sel_hi:[1,0,1]
	v_mov_b32_e32 v130, v131
	v_pk_fma_f32 v[138:139], v[76:77], v[130:131], v[138:139] op_sel_hi:[1,0,1]
	v_pk_fma_f32 v[128:129], v[78:79], v[130:131], v[128:129] op_sel_hi:[1,0,1]
	s_waitcnt lgkmcnt(0)
	v_pk_fma_f32 v[130:131], v[88:89], v[132:133], v[138:139] op_sel_hi:[1,0,1]
	ds_read_b128 v[138:141], v136 offset:2048
	v_pk_fma_f32 v[128:129], v[90:91], v[132:133], v[128:129] op_sel_hi:[1,0,1]
	v_pk_fma_f32 v[130:131], v[84:85], v[132:133], v[130:131] op_sel:[0,1,0]
	v_pk_fma_f32 v[128:129], v[86:87], v[132:133], v[128:129] op_sel:[0,1,0]
	s_add_i32 s0, s0, s1
	v_pk_fma_f32 v[132:133], v[98:99], v[134:135], v[128:129] op_sel_hi:[1,0,1]
	v_pk_fma_f32 v[128:129], v[96:97], v[134:135], v[130:131] op_sel_hi:[1,0,1]
	v_mov_b32_e32 v130, v135
	v_pk_fma_f32 v[128:129], v[72:73], v[130:131], v[128:129] op_sel_hi:[1,0,1]
	v_pk_fma_f32 v[132:133], v[74:75], v[130:131], v[132:133] op_sel_hi:[1,0,1]
	s_waitcnt lgkmcnt(0)
	v_pk_fma_f32 v[130:131], v[100:101], v[138:139], 0 op_sel_hi:[1,0,0]
	v_pk_fma_f32 v[134:135], v[102:103], v[138:139], 0 op_sel_hi:[1,0,0]
	v_pk_fma_f32 v[130:131], v[92:93], v[138:139], v[130:131] op_sel:[0,1,0]
	v_pk_fma_f32 v[134:135], v[94:95], v[138:139], v[134:135] op_sel:[0,1,0]
	v_pk_fma_f32 v[130:131], v[112:113], v[140:141], v[130:131] op_sel_hi:[1,0,1]
	v_pk_fma_f32 v[134:135], v[114:115], v[140:141], v[134:135] op_sel_hi:[1,0,1]
	v_mov_b32_e32 v138, v141
	v_pk_fma_f32 v[130:131], v[108:109], v[138:139], v[130:131] op_sel_hi:[1,0,1]
	v_pk_fma_f32 v[134:135], v[110:111], v[138:139], v[134:135] op_sel_hi:[1,0,1]
	ds_read_b128 v[138:141], v136 offset:2080
	v_pk_fma_f32 v[134:135], v[122:123], v[146:147], v[134:135] op_sel_hi:[1,0,1]
	v_pk_fma_f32 v[130:131], v[120:121], v[146:147], v[130:131] op_sel_hi:[1,0,1]
	v_pk_fma_f32 v[134:135], v[118:119], v[146:147], v[134:135] op_sel:[0,1,0]
	v_pk_fma_f32 v[130:131], v[116:117], v[146:147], v[130:131] op_sel:[0,1,0]
	v_pk_fma_f32 v[134:135], v[126:127], v[148:149], v[134:135] op_sel_hi:[1,0,1]
	v_pk_fma_f32 v[130:131], v[124:125], v[148:149], v[130:131] op_sel_hi:[1,0,1]
	v_mov_b32_e32 v146, v149
	v_pk_fma_f32 v[130:131], v[104:105], v[146:147], v[130:131] op_sel_hi:[1,0,1]
	v_pk_fma_f32 v[134:135], v[106:107], v[146:147], v[134:135] op_sel_hi:[1,0,1]
	ds_read_b128 v[146:149], v136 offset:2096
	s_waitcnt lgkmcnt(1)
	v_pk_fma_f32 v[134:135], v[70:71], v[138:139], v[134:135] op_sel_hi:[1,0,1]
	v_pk_fma_f32 v[130:131], v[68:69], v[138:139], v[130:131] op_sel_hi:[1,0,1]
	v_pk_fma_f32 v[134:135], v[66:67], v[138:139], v[134:135] op_sel:[0,1,0]
	v_pk_fma_f32 v[130:131], v[64:65], v[138:139], v[130:131] op_sel:[0,1,0]
	v_pk_fma_f32 v[134:135], v[82:83], v[140:141], v[134:135] op_sel_hi:[1,0,1]
	v_pk_fma_f32 v[130:131], v[80:81], v[140:141], v[130:131] op_sel_hi:[1,0,1]
	v_mov_b32_e32 v138, v141
	v_pk_fma_f32 v[130:131], v[76:77], v[138:139], v[130:131] op_sel_hi:[1,0,1]
	v_pk_fma_f32 v[134:135], v[78:79], v[138:139], v[134:135] op_sel_hi:[1,0,1]
	ds_read_b128 v[138:141], v136 offset:3072
	s_waitcnt lgkmcnt(1)
	v_pk_fma_f32 v[134:135], v[90:91], v[146:147], v[134:135] op_sel_hi:[1,0,1]
	v_pk_fma_f32 v[130:131], v[88:89], v[146:147], v[130:131] op_sel_hi:[1,0,1]
	v_pk_fma_f32 v[134:135], v[86:87], v[146:147], v[134:135] op_sel:[0,1,0]
	v_pk_fma_f32 v[130:131], v[84:85], v[146:147], v[130:131] op_sel:[0,1,0]
	v_pk_fma_f32 v[134:135], v[98:99], v[148:149], v[134:135] op_sel_hi:[1,0,1]
	v_pk_fma_f32 v[130:131], v[96:97], v[148:149], v[130:131] op_sel_hi:[1,0,1]
	v_mov_b32_e32 v146, v149
	v_pk_fma_f32 v[130:131], v[72:73], v[146:147], v[130:131] op_sel_hi:[1,0,1]
	v_pk_fma_f32 v[134:135], v[74:75], v[146:147], v[134:135] op_sel_hi:[1,0,1]
	ds_read_b128 v[146:149], v136 offset:3088
	s_waitcnt lgkmcnt(1)
; #define LAS __attribute__((address_space(3)))
; DI void attn_sample_item(const Params& p, int item, ldsp lds, int tid_) {
;     ...
; #pragma unroll
;     for (int t = 0; t < 4; ++t)
; #pragma unroll
;       for (int j4 = 0; j4 < 4; ++j4) { const f32x4 pp = *(const LAS f32x4*)(SC + t * 256 + wid * 32 + j4 * 4);
; #pragma unroll
;         for (int e = 0; e < 4; ++e) acc[t] += pp[e] * vvA[j4 * 4 + e]; }
; #pragma unroll
;     for (int t = 0; t < 4; ++t)
; #pragma unroll
;       for (int j4 = 0; j4 < 4; ++j4) { const f32x4 pp = *(const LAS f32x4*)(SC + t * 256 + wid * 32 + 16 + j4 * 4);
; #pragma unroll
;         for (int e = 0; e < 4; ++e) acc[t] += pp[e] * vvB[j4 * 4 + e]; }
	v_pk_fma_f32 v[100:101], v[100:101], v[138:139], 0 op_sel_hi:[1,0,0]
	v_pk_fma_f32 v[102:103], v[102:103], v[138:139], 0 op_sel_hi:[1,0,0]
	v_pk_fma_f32 v[92:93], v[92:93], v[138:139], v[100:101] op_sel:[0,1,0]
	v_pk_fma_f32 v[94:95], v[94:95], v[138:139], v[102:103] op_sel:[0,1,0]
	v_pk_fma_f32 v[92:93], v[112:113], v[140:141], v[92:93] op_sel_hi:[1,0,1]
	v_pk_fma_f32 v[94:95], v[114:115], v[140:141], v[94:95] op_sel_hi:[1,0,1]
	v_mov_b32_e32 v100, v141
	v_pk_fma_f32 v[92:93], v[108:109], v[100:101], v[92:93] op_sel_hi:[1,0,1]
	v_pk_fma_f32 v[94:95], v[110:111], v[100:101], v[94:95] op_sel_hi:[1,0,1]
	s_waitcnt lgkmcnt(0)
	v_pk_fma_f32 v[92:93], v[120:121], v[146:147], v[92:93] op_sel_hi:[1,0,1]
	v_pk_fma_f32 v[94:95], v[122:123], v[146:147], v[94:95] op_sel_hi:[1,0,1]
	v_pk_fma_f32 v[92:93], v[116:117], v[146:147], v[92:93] op_sel:[0,1,0]
	v_pk_fma_f32 v[94:95], v[118:119], v[146:147], v[94:95] op_sel:[0,1,0]
	v_pk_fma_f32 v[102:103], v[124:125], v[148:149], v[92:93] op_sel_hi:[1,0,1]
	v_pk_fma_f32 v[100:101], v[126:127], v[148:149], v[94:95] op_sel_hi:[1,0,1]
	ds_read_b128 v[92:95], v136 offset:3104
	v_mov_b32_e32 v108, v149
	v_pk_fma_f32 v[104:105], v[104:105], v[108:109], v[102:103] op_sel_hi:[1,0,1]
	v_pk_fma_f32 v[106:107], v[106:107], v[108:109], v[100:101] op_sel_hi:[1,0,1]
	ds_read_b128 v[100:103], v136 offset:3120
	s_waitcnt lgkmcnt(1)
	v_pk_fma_f32 v[70:71], v[70:71], v[92:93], v[106:107] op_sel_hi:[1,0,1]
	v_pk_fma_f32 v[68:69], v[68:69], v[92:93], v[104:105] op_sel_hi:[1,0,1]
	v_pk_fma_f32 v[66:67], v[66:67], v[92:93], v[70:71] op_sel:[0,1,0]
	v_pk_fma_f32 v[64:65], v[64:65], v[92:93], v[68:69] op_sel:[0,1,0]
	v_pk_fma_f32 v[66:67], v[82:83], v[94:95], v[66:67] op_sel_hi:[1,0,1]
	v_pk_fma_f32 v[64:65], v[80:81], v[94:95], v[64:65] op_sel_hi:[1,0,1]
	v_mov_b32_e32 v68, v95
	v_pk_fma_f32 v[64:65], v[76:77], v[68:69], v[64:65] op_sel_hi:[1,0,1]
	v_pk_fma_f32 v[66:67], v[78:79], v[68:69], v[66:67] op_sel_hi:[1,0,1]
	ds_read_b128 v[68:71], v136 offset:64
	s_waitcnt lgkmcnt(1)
	v_pk_fma_f32 v[66:67], v[90:91], v[100:101], v[66:67] op_sel_hi:[1,0,1]
	v_pk_fma_f32 v[64:65], v[88:89], v[100:101], v[64:65] op_sel_hi:[1,0,1]
	v_pk_fma_f32 v[66:67], v[86:87], v[100:101], v[66:67] op_sel:[0,1,0]
	v_pk_fma_f32 v[64:65], v[84:85], v[100:101], v[64:65] op_sel:[0,1,0]
	v_pk_fma_f32 v[66:67], v[98:99], v[102:103], v[66:67] op_sel_hi:[1,0,1]
	v_pk_fma_f32 v[64:65], v[96:97], v[102:103], v[64:65] op_sel_hi:[1,0,1]
	v_mov_b32_e32 v76, v103
	v_pk_fma_f32 v[64:65], v[72:73], v[76:77], v[64:65] op_sel_hi:[1,0,1]
	v_pk_fma_f32 v[66:67], v[74:75], v[76:77], v[66:67] op_sel_hi:[1,0,1]
	ds_read_b128 v[72:75], v136 offset:80
	s_waitcnt vmcnt(15) lgkmcnt(1)
	v_pk_fma_f32 v[76:77], v[42:43], v[68:69], v[150:151] op_sel_hi:[1,0,1]
	v_pk_fma_f32 v[78:79], v[40:41], v[68:69], v[142:143] op_sel_hi:[1,0,1]
	s_waitcnt vmcnt(14)
	v_pk_fma_f32 v[76:77], v[38:39], v[68:69], v[76:77] op_sel:[0,1,0]
	v_pk_fma_f32 v[68:69], v[36:37], v[68:69], v[78:79] op_sel:[0,1,0]
	s_waitcnt vmcnt(13)
	v_pk_fma_f32 v[76:77], v[50:51], v[70:71], v[76:77] op_sel_hi:[1,0,1]
	v_pk_fma_f32 v[68:69], v[48:49], v[70:71], v[68:69] op_sel_hi:[1,0,1]
	v_mov_b32_e32 v70, v71
	s_waitcnt vmcnt(12)
	v_pk_fma_f32 v[76:77], v[46:47], v[70:71], v[76:77] op_sel_hi:[1,0,1]
	v_pk_fma_f32 v[68:69], v[44:45], v[70:71], v[68:69] op_sel_hi:[1,0,1]
	s_waitcnt vmcnt(11) lgkmcnt(0)
	v_pk_fma_f32 v[70:71], v[58:59], v[72:73], v[76:77] op_sel_hi:[1,0,1]
	v_pk_fma_f32 v[68:69], v[56:57], v[72:73], v[68:69] op_sel_hi:[1,0,1]
	s_waitcnt vmcnt(10)
	v_pk_fma_f32 v[70:71], v[54:55], v[72:73], v[70:71] op_sel:[0,1,0]
	v_pk_fma_f32 v[68:69], v[52:53], v[72:73], v[68:69] op_sel:[0,1,0]
	s_waitcnt vmcnt(9)
	v_pk_fma_f32 v[72:73], v[62:63], v[74:75], v[70:71] op_sel_hi:[1,0,1]
	v_pk_fma_f32 v[76:77], v[60:61], v[74:75], v[68:69] op_sel_hi:[1,0,1]
	ds_read_b128 v[68:71], v136 offset:96
	v_mov_b32_e32 v74, v75
	s_waitcnt vmcnt(8)
	v_pk_fma_f32 v[78:79], v[34:35], v[74:75], v[72:73] op_sel_hi:[1,0,1]
	v_pk_fma_f32 v[76:77], v[32:33], v[74:75], v[76:77] op_sel_hi:[1,0,1]
	ds_read_b128 v[72:75], v136 offset:112
	s_waitcnt vmcnt(7) lgkmcnt(1)
	v_pk_fma_f32 v[78:79], v[14:15], v[68:69], v[78:79] op_sel_hi:[1,0,1]
	v_pk_fma_f32 v[76:77], v[12:13], v[68:69], v[76:77] op_sel_hi:[1,0,1]
	s_waitcnt vmcnt(6)
	v_pk_fma_f32 v[78:79], v[6:7], v[68:69], v[78:79] op_sel:[0,1,0]
	v_pk_fma_f32 v[68:69], v[4:5], v[68:69], v[76:77] op_sel:[0,1,0]
	s_waitcnt vmcnt(5)
	v_pk_fma_f32 v[76:77], v[22:23], v[70:71], v[78:79] op_sel_hi:[1,0,1]
	v_pk_fma_f32 v[68:69], v[20:21], v[70:71], v[68:69] op_sel_hi:[1,0,1]
	v_mov_b32_e32 v70, v71
	s_waitcnt vmcnt(4)
	v_pk_fma_f32 v[76:77], v[10:11], v[70:71], v[76:77] op_sel_hi:[1,0,1]
	v_pk_fma_f32 v[68:69], v[8:9], v[70:71], v[68:69] op_sel_hi:[1,0,1]
	s_waitcnt vmcnt(3) lgkmcnt(0)
	v_pk_fma_f32 v[70:71], v[26:27], v[72:73], v[76:77] op_sel_hi:[1,0,1]
	v_pk_fma_f32 v[68:69], v[24:25], v[72:73], v[68:69] op_sel_hi:[1,0,1]
	s_waitcnt vmcnt(2)
	v_pk_fma_f32 v[70:71], v[18:19], v[72:73], v[70:71] op_sel:[0,1,0]
	v_pk_fma_f32 v[68:69], v[16:17], v[72:73], v[68:69] op_sel:[0,1,0]
	s_waitcnt vmcnt(1)
	v_pk_fma_f32 v[72:73], v[30:31], v[74:75], v[70:71] op_sel_hi:[1,0,1]
	v_pk_fma_f32 v[76:77], v[28:29], v[74:75], v[68:69] op_sel_hi:[1,0,1]
	ds_read_b128 v[68:71], v136 offset:1088
	v_mov_b32_e32 v78, v75
	s_waitcnt vmcnt(0)
	v_pk_fma_f32 v[74:75], v[2:3], v[78:79], v[72:73] op_sel_hi:[1,0,1]
	v_pk_fma_f32 v[72:73], v[0:1], v[78:79], v[76:77] op_sel_hi:[1,0,1]
	ds_read_b128 v[76:79], v136 offset:1104
	s_waitcnt lgkmcnt(1)
; #define LAS __attribute__((address_space(3)))
; DI void attn_sample_item(const Params& p, int item, ldsp lds, int tid_) {
;     ...
;     for (int t = 0; t < 4; ++t)
; #pragma unroll
;       for (int j4 = 0; j4 < 4; ++j4) { const f32x4 pp = *(const LAS f32x4*)(SC + t * 256 + wid * 32 + 16 + j4 * 4);
; #pragma unroll
;         for (int e = 0; e < 4; ++e) acc[t] += pp[e] * vvB[j4 * 4 + e]; }
	v_pk_fma_f32 v[80:81], v[42:43], v[68:69], v[132:133] op_sel_hi:[1,0,1]
	v_pk_fma_f32 v[82:83], v[40:41], v[68:69], v[128:129] op_sel_hi:[1,0,1]
	v_pk_fma_f32 v[80:81], v[38:39], v[68:69], v[80:81] op_sel:[0,1,0]
	v_pk_fma_f32 v[68:69], v[36:37], v[68:69], v[82:83] op_sel:[0,1,0]
	v_pk_fma_f32 v[80:81], v[50:51], v[70:71], v[80:81] op_sel_hi:[1,0,1]
	v_pk_fma_f32 v[68:69], v[48:49], v[70:71], v[68:69] op_sel_hi:[1,0,1]
	v_mov_b32_e32 v70, v71
	v_pk_fma_f32 v[80:81], v[46:47], v[70:71], v[80:81] op_sel_hi:[1,0,1]
	v_pk_fma_f32 v[68:69], v[44:45], v[70:71], v[68:69] op_sel_hi:[1,0,1]
	s_waitcnt lgkmcnt(0)
	v_pk_fma_f32 v[70:71], v[58:59], v[76:77], v[80:81] op_sel_hi:[1,0,1]
	v_pk_fma_f32 v[68:69], v[56:57], v[76:77], v[68:69] op_sel_hi:[1,0,1]
	v_pk_fma_f32 v[70:71], v[54:55], v[76:77], v[70:71] op_sel:[0,1,0]
	v_pk_fma_f32 v[68:69], v[52:53], v[76:77], v[68:69] op_sel:[0,1,0]
	v_pk_fma_f32 v[76:77], v[62:63], v[78:79], v[70:71] op_sel_hi:[1,0,1]
	v_pk_fma_f32 v[80:81], v[60:61], v[78:79], v[68:69] op_sel_hi:[1,0,1]
	ds_read_b128 v[68:71], v136 offset:1120
	v_mov_b32_e32 v78, v79
	v_pk_fma_f32 v[82:83], v[34:35], v[78:79], v[76:77] op_sel_hi:[1,0,1]
	v_pk_fma_f32 v[80:81], v[32:33], v[78:79], v[80:81] op_sel_hi:[1,0,1]
	ds_read_b128 v[76:79], v136 offset:1136
	s_waitcnt lgkmcnt(1)
	v_pk_fma_f32 v[82:83], v[14:15], v[68:69], v[82:83] op_sel_hi:[1,0,1]
	v_pk_fma_f32 v[80:81], v[12:13], v[68:69], v[80:81] op_sel_hi:[1,0,1]
	v_pk_fma_f32 v[82:83], v[6:7], v[68:69], v[82:83] op_sel:[0,1,0]
	v_pk_fma_f32 v[68:69], v[4:5], v[68:69], v[80:81] op_sel:[0,1,0]
	v_pk_fma_f32 v[80:81], v[22:23], v[70:71], v[82:83] op_sel_hi:[1,0,1]
	v_pk_fma_f32 v[68:69], v[20:21], v[70:71], v[68:69] op_sel_hi:[1,0,1]
	v_mov_b32_e32 v70, v71
	v_pk_fma_f32 v[80:81], v[10:11], v[70:71], v[80:81] op_sel_hi:[1,0,1]
	v_pk_fma_f32 v[68:69], v[8:9], v[70:71], v[68:69] op_sel_hi:[1,0,1]
	s_waitcnt lgkmcnt(0)
	v_pk_fma_f32 v[70:71], v[26:27], v[76:77], v[80:81] op_sel_hi:[1,0,1]
	v_pk_fma_f32 v[68:69], v[24:25], v[76:77], v[68:69] op_sel_hi:[1,0,1]
	v_pk_fma_f32 v[70:71], v[18:19], v[76:77], v[70:71] op_sel:[0,1,0]
	v_pk_fma_f32 v[68:69], v[16:17], v[76:77], v[68:69] op_sel:[0,1,0]
	v_pk_fma_f32 v[76:77], v[30:31], v[78:79], v[70:71] op_sel_hi:[1,0,1]
	v_pk_fma_f32 v[80:81], v[28:29], v[78:79], v[68:69] op_sel_hi:[1,0,1]
	ds_read_b128 v[68:71], v136 offset:2112
	v_mov_b32_e32 v82, v79
	v_pk_fma_f32 v[78:79], v[2:3], v[82:83], v[76:77] op_sel_hi:[1,0,1]
	v_pk_fma_f32 v[76:77], v[0:1], v[82:83], v[80:81] op_sel_hi:[1,0,1]
	ds_read_b128 v[80:83], v136 offset:2128
	s_waitcnt lgkmcnt(1)
	v_pk_fma_f32 v[84:85], v[42:43], v[68:69], v[134:135] op_sel_hi:[1,0,1]
	v_pk_fma_f32 v[86:87], v[40:41], v[68:69], v[130:131] op_sel_hi:[1,0,1]
	v_pk_fma_f32 v[84:85], v[38:39], v[68:69], v[84:85] op_sel:[0,1,0]
	v_pk_fma_f32 v[68:69], v[36:37], v[68:69], v[86:87] op_sel:[0,1,0]
	v_pk_fma_f32 v[84:85], v[50:51], v[70:71], v[84:85] op_sel_hi:[1,0,1]
	v_pk_fma_f32 v[68:69], v[48:49], v[70:71], v[68:69] op_sel_hi:[1,0,1]
	v_mov_b32_e32 v70, v71
	v_pk_fma_f32 v[84:85], v[46:47], v[70:71], v[84:85] op_sel_hi:[1,0,1]
	v_pk_fma_f32 v[68:69], v[44:45], v[70:71], v[68:69] op_sel_hi:[1,0,1]
	s_waitcnt lgkmcnt(0)
	v_pk_fma_f32 v[70:71], v[58:59], v[80:81], v[84:85] op_sel_hi:[1,0,1]
	v_pk_fma_f32 v[68:69], v[56:57], v[80:81], v[68:69] op_sel_hi:[1,0,1]
	v_pk_fma_f32 v[70:71], v[54:55], v[80:81], v[70:71] op_sel:[0,1,0]
	v_pk_fma_f32 v[68:69], v[52:53], v[80:81], v[68:69] op_sel:[0,1,0]
	v_pk_fma_f32 v[80:81], v[62:63], v[82:83], v[70:71] op_sel_hi:[1,0,1]
	v_pk_fma_f32 v[84:85], v[60:61], v[82:83], v[68:69] op_sel_hi:[1,0,1]
	ds_read_b128 v[68:71], v136 offset:2144
	v_mov_b32_e32 v82, v83
	v_pk_fma_f32 v[86:87], v[34:35], v[82:83], v[80:81] op_sel_hi:[1,0,1]
	v_pk_fma_f32 v[84:85], v[32:33], v[82:83], v[84:85] op_sel_hi:[1,0,1]
	ds_read_b128 v[80:83], v136 offset:2160
	s_waitcnt lgkmcnt(1)
	v_pk_fma_f32 v[86:87], v[14:15], v[68:69], v[86:87] op_sel_hi:[1,0,1]
	v_pk_fma_f32 v[84:85], v[12:13], v[68:69], v[84:85] op_sel_hi:[1,0,1]
	v_pk_fma_f32 v[86:87], v[6:7], v[68:69], v[86:87] op_sel:[0,1,0]
	v_pk_fma_f32 v[68:69], v[4:5], v[68:69], v[84:85] op_sel:[0,1,0]
	v_pk_fma_f32 v[84:85], v[22:23], v[70:71], v[86:87] op_sel_hi:[1,0,1]
	v_pk_fma_f32 v[68:69], v[20:21], v[70:71], v[68:69] op_sel_hi:[1,0,1]
	v_mov_b32_e32 v70, v71
	v_pk_fma_f32 v[84:85], v[10:11], v[70:71], v[84:85] op_sel_hi:[1,0,1]
	v_pk_fma_f32 v[68:69], v[8:9], v[70:71], v[68:69] op_sel_hi:[1,0,1]
	s_waitcnt lgkmcnt(0)
; #define LAS __attribute__((address_space(3)))
; DI unsigned pk2(float lo, float hi) { f32x2 v = {lo, hi}; return __builtin_bit_cast(unsigned, __builtin_convertvector(v, bf16x2v)); }
; DI void lbar() { asm volatile("s_waitcnt lgkmcnt(0)" ::: "memory"); __builtin_amdgcn_s_barrier(); asm volatile("" ::: "memory"); }
; DI void attn_sample_item(const Params& p, int item, ldsp lds, int tid_) {
;     ...
;     for (int t = 0; t < 4; ++t)
; #pragma unroll
;       for (int j4 = 0; j4 < 4; ++j4) { const f32x4 pp = *(const LAS f32x4*)(SC + t * 256 + wid * 32 + 16 + j4 * 4);
; #pragma unroll
;         for (int e = 0; e < 4; ++e) acc[t] += pp[e] * vvB[j4 * 4 + e]; }
; #pragma unroll
;     for (int t = 0; t < 4; ++t) *(LAS f32x4*)(PART + (wid * 4 + t) * 256 + lane * 4) = acc[t];
;   }
;   lbar();
;   {
;     const int e0 = tid * 2, t = e0 >> 8, d = e0 & 255;
;     float s0 = 0.f, s1 = 0.f;
; #pragma unroll
;     for (int w = 0; w < 8; ++w) { const f32x2 v = *(const LAS f32x2*)(PART + (w * 4 + t) * 256 + d); s0 += v[0]; s1 += v[1]; }
;     *(unsigned*)((bf16_t*)(p.ws + B_XA) + (size_t)(TP + b * 4 + t) * D + h * 256 + d) = pk2(s0, s1);
;   }
;   lbar();
; DI void phase_attn(const Params& p, ldsp lds, int tid) {
;     ...
;   if (blockIdx.x & 1) for (int j = blockIdx.x; j < 512; j += G) attn_sample_item(p, j, lds, tid);
	v_pk_fma_f32 v[70:71], v[26:27], v[80:81], v[84:85] op_sel_hi:[1,0,1]
	v_pk_fma_f32 v[68:69], v[24:25], v[80:81], v[68:69] op_sel_hi:[1,0,1]
	v_pk_fma_f32 v[70:71], v[18:19], v[80:81], v[70:71] op_sel:[0,1,0]
	v_pk_fma_f32 v[68:69], v[16:17], v[80:81], v[68:69] op_sel:[0,1,0]
	v_pk_fma_f32 v[80:81], v[30:31], v[82:83], v[70:71] op_sel_hi:[1,0,1]
	v_pk_fma_f32 v[84:85], v[28:29], v[82:83], v[68:69] op_sel_hi:[1,0,1]
	ds_read_b128 v[68:71], v136 offset:3136
	v_mov_b32_e32 v86, v83
	v_pk_fma_f32 v[82:83], v[2:3], v[86:87], v[80:81] op_sel_hi:[1,0,1]
	v_pk_fma_f32 v[80:81], v[0:1], v[86:87], v[84:85] op_sel_hi:[1,0,1]
	ds_read_b128 v[84:87], v136 offset:3152
	s_waitcnt lgkmcnt(1)
	v_pk_fma_f32 v[42:43], v[42:43], v[68:69], v[66:67] op_sel_hi:[1,0,1]
	v_pk_fma_f32 v[40:41], v[40:41], v[68:69], v[64:65] op_sel_hi:[1,0,1]
	v_pk_fma_f32 v[38:39], v[38:39], v[68:69], v[42:43] op_sel:[0,1,0]
	v_pk_fma_f32 v[36:37], v[36:37], v[68:69], v[40:41] op_sel:[0,1,0]
	v_pk_fma_f32 v[38:39], v[50:51], v[70:71], v[38:39] op_sel_hi:[1,0,1]
	v_pk_fma_f32 v[36:37], v[48:49], v[70:71], v[36:37] op_sel_hi:[1,0,1]
	v_mov_b32_e32 v40, v71
	v_pk_fma_f32 v[38:39], v[46:47], v[40:41], v[38:39] op_sel_hi:[1,0,1]
	v_pk_fma_f32 v[36:37], v[44:45], v[40:41], v[36:37] op_sel_hi:[1,0,1]
	s_waitcnt lgkmcnt(0)
	v_pk_fma_f32 v[38:39], v[58:59], v[84:85], v[38:39] op_sel_hi:[1,0,1]
	v_pk_fma_f32 v[36:37], v[56:57], v[84:85], v[36:37] op_sel_hi:[1,0,1]
	v_pk_fma_f32 v[38:39], v[54:55], v[84:85], v[38:39] op_sel:[0,1,0]
	v_pk_fma_f32 v[36:37], v[52:53], v[84:85], v[36:37] op_sel:[0,1,0]
	v_pk_fma_f32 v[40:41], v[62:63], v[86:87], v[38:39] op_sel_hi:[1,0,1]
	v_pk_fma_f32 v[42:43], v[60:61], v[86:87], v[36:37] op_sel_hi:[1,0,1]
	ds_read_b128 v[36:39], v136 offset:3168
	v_mov_b32_e32 v44, v87
	v_pk_fma_f32 v[40:41], v[34:35], v[44:45], v[40:41] op_sel_hi:[1,0,1]
	v_pk_fma_f32 v[42:43], v[32:33], v[44:45], v[42:43] op_sel_hi:[1,0,1]
	ds_read_b128 v[32:35], v136 offset:3184
	s_waitcnt lgkmcnt(1)
	v_pk_fma_f32 v[12:13], v[12:13], v[36:37], v[42:43] op_sel_hi:[1,0,1]
	v_pk_fma_f32 v[14:15], v[14:15], v[36:37], v[40:41] op_sel_hi:[1,0,1]
	v_pk_fma_f32 v[4:5], v[4:5], v[36:37], v[12:13] op_sel:[0,1,0]
	v_mov_b32_e32 v12, v39
	v_pk_fma_f32 v[4:5], v[20:21], v[38:39], v[4:5] op_sel_hi:[1,0,1]
	v_pk_fma_f32 v[6:7], v[6:7], v[36:37], v[14:15] op_sel:[0,1,0]
	v_pk_fma_f32 v[4:5], v[8:9], v[12:13], v[4:5] op_sel_hi:[1,0,1]
	v_pk_fma_f32 v[6:7], v[22:23], v[38:39], v[6:7] op_sel_hi:[1,0,1]
	s_waitcnt lgkmcnt(0)
	v_pk_fma_f32 v[4:5], v[24:25], v[32:33], v[4:5] op_sel_hi:[1,0,1]
	v_pk_fma_f32 v[6:7], v[10:11], v[12:13], v[6:7] op_sel_hi:[1,0,1]
	v_pk_fma_f32 v[4:5], v[16:17], v[32:33], v[4:5] op_sel:[0,1,0]
	v_pk_fma_f32 v[6:7], v[26:27], v[32:33], v[6:7] op_sel_hi:[1,0,1]
	v_pk_fma_f32 v[4:5], v[28:29], v[34:35], v[4:5] op_sel_hi:[1,0,1]
	v_mov_b32_e32 v8, v35
	v_pk_fma_f32 v[6:7], v[18:19], v[32:33], v[6:7] op_sel:[0,1,0]
	v_pk_fma_f32 v[0:1], v[0:1], v[8:9], v[4:5] op_sel_hi:[1,0,1]
	v_lshlrev_b32_e32 v4, 12, v210
	v_pk_fma_f32 v[6:7], v[30:31], v[34:35], v[6:7] op_sel_hi:[1,0,1]
	v_add3_u32 v4, 16, v4, v144
	v_pk_fma_f32 v[2:3], v[2:3], v[8:9], v[6:7] op_sel_hi:[1,0,1]
	ds_write_b128 v4, v[72:75] offset:4096
	ds_write_b128 v4, v[76:79] offset:5120
	ds_write_b128 v4, v[80:83] offset:6144
	ds_write_b128 v4, v[0:3] offset:7168
	v_lshlrev_b32_e32 v0, 1, v222
	v_ashrrev_i32_e32 v16, 7, v222
	v_and_b32_e32 v17, 0xfe, v0
	v_lshlrev_b32_e32 v0, 10, v16
	v_lshlrev_b32_e32 v1, 2, v17
	s_waitcnt lgkmcnt(0)
	s_barrier
	v_add3_u32 v12, 16, v0, v1
	ds_read2st64_b64 v[0:3], v12 offset0:8 offset1:16
	ds_read2st64_b64 v[4:7], v12 offset0:24 offset1:32
	ds_read2st64_b64 v[8:11], v12 offset0:40 offset1:48
	ds_read2st64_b64 v[12:15], v12 offset0:56 offset1:64
	v_lshlrev_b32_e32 v144, 1, v17
	s_waitcnt lgkmcnt(3)
	v_pk_add_f32 v[0:1], v[0:1], 0 op_sel_hi:[1,0]
	s_cmp_lt_i32 s40, s99
	v_pk_add_f32 v[0:1], v[0:1], v[2:3]
	s_waitcnt lgkmcnt(2)
	v_pk_add_f32 v[0:1], v[0:1], v[4:5]
	s_nop 0
	v_pk_add_f32 v[0:1], v[0:1], v[6:7]
	s_waitcnt lgkmcnt(1)
	v_pk_add_f32 v[0:1], v[0:1], v[8:9]
	s_nop 0
	v_pk_add_f32 v[0:1], v[0:1], v[10:11]
	s_waitcnt lgkmcnt(0)
	v_pk_add_f32 v[0:1], v[0:1], v[12:13]
	s_nop 0
	v_pk_add_f32 v[0:1], v[0:1], v[14:15]
	s_nop 0
	v_cvt_pk_bf16_f32 v2, v0, v1
	v_add_u32_e32 v0, s4, v16
	v_ashrrev_i32_e32 v1, 31, v0
	v_lshlrev_b64 v[0:1], 11, v[0:1]
	v_lshl_add_u64 v[0:1], s[22:23], 0, v[0:1]
	v_lshl_add_u64 v[0:1], v[0:1], 0, s[26:27]
	v_lshl_add_u64 v[0:1], v[0:1], 0, v[144:145]
	global_store_dword v[0:1], v2, off
	s_waitcnt lgkmcnt(0)
	s_barrier
	s_cbranch_scc0 .LBB0_1670

; DI void phase_attn(const Params& p, ldsp lds, int tid) {
;     ...
;   if (!(blockIdx.x & 1)) for (int j = blockIdx.x; j < 512; j += G) attn_sample_item(p, j, lds, tid);
.LBB0_1673:
	s_cmpk_gt_i32 s2, 0x1ff
	s_cselect_b64 s[0:1], -1, 0
	s_cmp_eq_u32 s98, 0
	s_cselect_b64 s[4:5], -1, 0
	s_or_b64 s[0:1], s[0:1], s[4:5]
	s_and_b64 vcc, exec, s[0:1]
	s_cbranch_vccnz .LBB0_1742
	v_mbcnt_hi_u32_b32 v214, -1, v213
	v_and_b32_e32 v0, 64, v214
	s_lshl_b32 s0, s2, 8
	s_lshl_b32 s1, s94, 8
	s_mov_b32 s25, 0
	v_mov_b32_e32 v145, 0
	s_mov_b32 s3, 0x200000
	s_mov_b32 s33, 0x400000
	s_mov_b32 s34, 0x600000
	v_xor_b32_e32 v215, 1, v214
	v_add_u32_e32 v216, 64, v0
	v_xor_b32_e32 v217, 2, v214
	v_xor_b32_e32 v218, 4, v214
	v_xor_b32_e32 v219, 8, v214
	v_xor_b32_e32 v220, 16, v214
	v_xor_b32_e32 v221, 32, v214
	s_mov_b32 s35, 0xf149f2ca
	s_mov_b32 s38, s2
	s_cmp_eq_u32 s98, 2
	s_cselect_b32 s4, s94, 0
	s_add_i32 s38, s38, s4
	s_lshl_b32 s0, s38, 8
	s_branch .LBB0_1676
